# all remaining compiled grid barriers (except the first, census) replaced by a leaner one: fresh counters, every block polls the top counter directly
# speedup vs baseline: 1.0069x; 1.0009x over previous
.LBB0_181:
	s_cmp_gt_i32 s97, 2
	s_cselect_b64 s[0:1], -1, 0
	s_and_b64 s[4:5], s[4:5], s[0:1]
	s_andn2_b64 vcc, exec, s[4:5]
	v_writelane_b32 v254, s44, 45
	s_cbranch_vccnz .LBB0_235
	s_waitcnt vmcnt(0) lgkmcnt(0)
	s_barrier
	s_mov_b64 s[4:5], exec
	v_readlane_b32 s6, v254, 2
	v_readlane_b32 s7, v254, 3
	s_nop 1
	s_and_b64 s[6:7], s[4:5], s[6:7]
	s_mov_b64 exec, s[6:7]
	s_cbranch_execz .Llb182_join
	s_getreg_b32 s8, hwreg(HW_REG_XCC_ID, 0, 4)
	v_mov_b32_e32 v1, 0x23fc0
	ds_read_b64 v[16:17], v1
	s_lshl_b32 s8, s8, 6
	s_add_u32 s10, s62, 0x40a000
	s_addc_u32 s11, s63, 0
	v_mov_b32_e32 v1, s8
	v_mov_b32_e32 v3, 1
	global_atomic_add v2, v1, v3, s[10:11] sc0
	s_waitcnt vmcnt(0) lgkmcnt(0)
	v_add_u32_e32 v2, 1, v2
	v_cmp_eq_u32_e32 vcc, v2, v16
	v_mov_b32_e32 v1, 0x400
	s_cbranch_vccz .Llb182_poll
	buffer_wbl2 sc1
	s_waitcnt vmcnt(0)
	global_atomic_add v1, v3, s[10:11]
.Llb182_poll:
	s_mov_b32 s9, 0
.Llb182_spin:
	global_load_dword v2, v1, s[10:11] sc1
	s_waitcnt vmcnt(0)
	v_cmp_ge_u32_e32 vcc, v2, v17
	s_cbranch_vccnz .Llb182_done
	s_sleep 1
	s_add_u32 s9, s9, 1
	s_cmp_lt_u32 s9, 0x100000
	s_cbranch_scc1 .Llb182_spin

.LBB0_286:
	s_cmp_gt_i32 s97, 3
	s_cselect_b64 s[4:5], -1, 0
	s_and_b64 s[0:1], s[0:1], s[4:5]
	s_andn2_b64 vcc, exec, s[0:1]
	s_cbranch_vccnz .LBB0_340
	s_waitcnt vmcnt(0) lgkmcnt(0)
	s_barrier
	s_mov_b64 s[0:1], exec
	v_readlane_b32 s6, v254, 2
	v_readlane_b32 s7, v254, 3
	s_nop 1
	s_and_b64 s[6:7], s[0:1], s[6:7]
	s_mov_b64 exec, s[6:7]
	s_cbranch_execz .Llb287_join
	s_getreg_b32 s8, hwreg(HW_REG_XCC_ID, 0, 4)
	v_mov_b32_e32 v1, 0x23fc0
	ds_read_b64 v[16:17], v1
	s_lshl_b32 s8, s8, 6
	s_add_u32 s10, s62, 0x40a800
	s_addc_u32 s11, s63, 0
	v_mov_b32_e32 v1, s8
	v_mov_b32_e32 v3, 1
	global_atomic_add v2, v1, v3, s[10:11] sc0
	s_waitcnt vmcnt(0) lgkmcnt(0)
	v_add_u32_e32 v2, 1, v2
	v_cmp_eq_u32_e32 vcc, v2, v16
	v_mov_b32_e32 v1, 0x400
	s_cbranch_vccz .Llb287_poll
	buffer_wbl2 sc1
	s_waitcnt vmcnt(0)
	global_atomic_add v1, v3, s[10:11]

.Llb287_join:
	s_mov_b64 exec, s[0:1]
	s_barrier
.LBB0_340:
	s_cmp_lt_i32 s96, 4
	s_cselect_b64 s[0:1], -1, 0
	s_and_b64 s[8:9], s[0:1], s[4:5]
	s_andn2_b64 vcc, exec, s[8:9]
	s_cbranch_vccnz .LBB0_393
	v_cmp_gt_u32_e32 vcc, 2, v190
	s_and_saveexec_b64 s[0:1], vcc
	v_lshlrev_b32_e32 v2, 2, v190
	v_add_u32_e32 v2, 0x21000, v2
	v_mov_b32_e32 v3, 0
	ds_write_b32 v2, v3
	s_mov_b64 exec, s[0:1]
	v_and_b32_e32 v172, 31, v191
	v_lshrrev_b32_e32 v173, 5, v191
	v_and_b32_e32 v174, 1, v191
	v_and_b32_e32 v175, 15, v191
	v_lshrrev_b32_e32 v176, 4, v191
	s_mul_i32 s20, s89, 0x3200
	v_lshl_add_u32 v151, v191, 2, s20
	v_mul_u32_u24_e32 v182, 0x110, v175
	v_lshl_add_u32 v182, v176, 4, v182
	v_add_u32_e32 v152, s20, v182
	v_lshlrev_b32_e32 v182, 5, v172
	v_lshl_add_u32 v150, v173, 4, v182
	v_xor_b32_e32 v193, 0x80, v150
	s_mov_b32 s66, 0x0f0f0f0f
	s_mov_b32 s67, 0x0f0f0f0f
	s_mov_b32 s68, 0xf0f0f0f0
	s_mov_b32 s69, 0xf0f0f0f0
	v_lshlrev_b32_e32 v182, 5, v172
	v_lshl_add_u32 v182, v173, 4, v182
	s_add_u32 s22, s20, 0x2200
	v_add_u32_e32 v162, s22, v182
	v_lshlrev_b32_e32 v182, 5, v175
	v_lshl_add_u32 v182, v176, 3, v182
	v_add_u32_e32 v163, s22, v182
	v_mul_u32_u24_e32 v182, 0x1800, v175
	v_lshl_add_u32 v154, v176, 3, v182
	v_add_u32_e32 v158, 0x18000, v154
	v_lshlrev_b32_e32 v182, 12, v175
	v_lshlrev_b32_e32 v182, 6, v175
	v_lshl_add_u32 v153, v176, 4, v182
	v_add_u32_e32 v157, 0x400, v153
	v_lshlrev_b32_e32 v182, 11, v175
	v_lshl_add_u32 v156, v176, 3, v182
	v_add_u32_e32 v159, 0x8000, v156
	s_and_b32 s21, s89, 3
	s_lshl_b32 s21, s21, 13
	s_add_u32 s21, s21, 0x19000
	v_lshlrev_b32_e32 v182, 5, v175
	v_lshl_add_u32 v182, v176, 3, v182
	v_add_u32_e32 v155, s21, v182
	v_lshrrev_b32_e32 v182, 3, v172
	v_lshlrev_b32_e32 v182, 10, v182
	v_and_b32_e32 v183, 7, v172
	v_lshl_add_u32 v182, v183, 5, v182
	v_lshl_add_u32 v177, v173, 8, v182
	v_lshlrev_b32_e32 v178, 4, v191
	v_lshlrev_b32_e32 v179, 3, v191
	v_lshlrev_b32_e32 v180, 2, v191
	v_add_u32_e32 v170, 0x4000, v180
	v_lshlrev_b32_e32 v181, 4, v176
	v_mov_b32_e32 v1, 0x3dd2d3e8
	s_waitcnt vmcnt(0) lgkmcnt(0)
	s_barrier
	s_cmp_lt_u32 s89, 4
	s_cbranch_scc0 .Lssm_ctx
	s_lshr_b32 s21, s89, 1
	s_and_b32 s22, s2, 7
	s_lshl_b32 s22, s22, 6
	s_lshr_b32 s26, s2, 3
	s_lshl_b32 s26, s26, 1
	s_add_u32 s22, s22, s26
	s_add_u32 s22, s22, s21
	s_lshr_b32 s23, s22, 6
	s_and_b32 s24, s22, 63
	s_lshl_b32 s25, s23, 10
	s_add_u32 s25, s25, 0x2000
	s_and_b32 s26, s89, 1
	s_cmp_eq_u32 s26, 0
	s_cbranch_scc0 .Lssm_lat_bwd
	s_add_u32 s28, s24, 0
	s_lshl_b32 s29, s28, 13
	s_add_u32 s29, s29, 0x200000
	s_add_u32 s10, s62, s29
	s_addc_u32 s11, s63, 0
	global_load_dwordx4 v[84:87], v177, s[10:11]
	global_load_dwordx4 v[88:91], v177, s[10:11] offset:16
	s_add_u32 s12, s10, 0x1000
	s_addc_u32 s13, s11, 0
	global_load_dwordx4 v[92:95], v177, s[12:13]
	global_load_dwordx4 v[96:99], v177, s[12:13] offset:16
	s_lshl_b32 s29, s28, 12
	s_add_u32 s29, s29, 0x300000
	s_add_u32 s16, s62, s29
	s_addc_u32 s17, s63, 0
	global_load_dwordx4 v[100:103], v178, s[16:17]
	global_load_dwordx4 v[104:107], v178, s[16:17] offset:1024
	global_load_dwordx4 v[108:111], v178, s[16:17] offset:2048
	global_load_dwordx4 v[112:115], v178, s[16:17] offset:3072
	s_lshl_b32 s29, s28, 9
	s_add_u32 s29, s29, 0x100000
	s_add_u32 s18, s62, s29
	s_addc_u32 s19, s63, 0
	global_load_dwordx2 v[116:117], v179, s[18:19]
	s_lshl_b32 s30, s23, 1
	s_lshl_b32 s30, s30, 15
	s_lshl_b32 s31, s24, 8
	s_add_u32 s30, s30, s31
	v_readlane_b32 s34, v254, 10
	v_readlane_b32 s35, v254, 11
	s_nop 3
	s_add_u32 s34, s34, s30
	s_addc_u32 s35, s35, 0
	global_load_dword v120, v180, s[34:35]
	global_load_dword v121, v170, s[34:35]
	v_readlane_b32 s34, v254, 28
	v_readlane_b32 s35, v254, 29
	s_nop 3
	s_lshl_b32 s31, s24, 6
	s_add_u32 s34, s34, s31
	s_addc_u32 s35, s35, 0
	global_load_dwordx4 v[164:167], v181, s[34:35]
	s_lshl_b32 s31, s25, 5
	s_lshl_b32 s29, s24, 19
	s_add_u32 s31, s31, s29
	s_add_u32 s31, s31, 0x16800000
	s_add_u32 s4, s62, s31
	s_addc_u32 s5, s63, 0
	s_lshl_b32 s31, s22, 1
	s_lshl_b32 s31, s31, 15
	s_add_u32 s31, s31, 0x4800000
	s_add_u32 s6, s62, s31
	s_addc_u32 s7, s63, 0
	s_add_u32 s34, s4, 0
	s_addc_u32 s35, s5, 0
	global_load_dwordx4 v[80:83], v150, s[34:35]
	global_load_dwordx4 v[194:197], v193, s[34:35]
	s_mov_b64 s[10:11], s[34:35]
	s_add_u32 s10, s10, 1024
	s_addc_u32 s11, s11, 0
	global_load_dwordx4 v[144:147], v150, s[10:11]
	global_load_dwordx4 v[168:171], v193, s[10:11]
	s_mov_b64 s[34:35], s[10:11]
	s_add_u32 s10, s10, 1024
	s_addc_u32 s11, s11, 0
	s_add_u32 s12, s6, 0
	s_addc_u32 s13, s7, 0
	s_mov_b32 s14, 0
	s_mov_b32 s40, 0xffff0000
	s_waitcnt vmcnt(0)
	v_xor_b32_e32 v118, 0x80000000, v117

.LBB0_393:
	s_cmp_gt_i32 s97, 4
	s_cselect_b64 s[0:1], -1, 0
	s_and_b64 s[4:5], s[8:9], s[0:1]
	v_readlane_b32 s72, v254, 22
	s_andn2_b64 vcc, exec, s[4:5]
	v_readlane_b32 s82, v254, 32
	v_readlane_b32 s83, v254, 33
	v_readlane_b32 s86, v254, 36
	v_readlane_b32 s87, v254, 37
	v_readlane_b32 s73, v254, 23
	v_readlane_b32 s74, v254, 24
	v_readlane_b32 s75, v254, 25
	v_readlane_b32 s76, v254, 26
	v_readlane_b32 s77, v254, 27
	v_readlane_b32 s78, v254, 28
	v_readlane_b32 s79, v254, 29
	v_readlane_b32 s80, v254, 30
	v_readlane_b32 s81, v254, 31
	v_readlane_b32 s84, v254, 34
	v_readlane_b32 s85, v254, 35
	s_cbranch_vccnz .LBB0_447
	s_waitcnt vmcnt(0) lgkmcnt(0)
	s_barrier
	s_mov_b64 s[4:5], exec
	v_readlane_b32 s6, v254, 2
	v_readlane_b32 s7, v254, 3
	s_nop 1
	s_and_b64 s[6:7], s[4:5], s[6:7]
	s_mov_b64 exec, s[6:7]
	s_cbranch_execz .Llb394_join
	s_getreg_b32 s3, hwreg(HW_REG_XCC_ID, 0, 4)
	v_mov_b32_e32 v1, 0x23fc0
	ds_read_b64 v[16:17], v1
	s_lshl_b32 s3, s3, 6
	s_add_u32 s10, s62, 0x40b000
	s_addc_u32 s11, s63, 0
	v_mov_b32_e32 v1, s3
	v_mov_b32_e32 v3, 1
	global_atomic_add v2, v1, v3, s[10:11] sc0
	s_waitcnt vmcnt(0) lgkmcnt(0)
	v_add_u32_e32 v2, 1, v2
	v_cmp_eq_u32_e32 vcc, v2, v16
	v_mov_b32_e32 v1, 0x400
	s_cbranch_vccz .Llb394_poll
	buffer_wbl2 sc1
	s_waitcnt vmcnt(0)
	global_atomic_add v1, v3, s[10:11]
.Llb394_poll:
	s_mov_b32 s8, 0
.Llb394_spin:
	global_load_dword v2, v1, s[10:11] sc1
	s_waitcnt vmcnt(0)
	v_cmp_ge_u32_e32 vcc, v2, v17
	s_cbranch_vccnz .Llb394_done
	s_sleep 1
	s_add_u32 s8, s8, 1
	s_cmp_lt_u32 s8, 0x100000
	s_cbranch_scc1 .Llb394_spin

.LBB0_486:
	s_cmp_gt_u32 s97, 5
	s_cselect_b64 s[4:5], -1, 0
	s_and_b64 s[0:1], s[0:1], s[4:5]
	s_andn2_b64 vcc, exec, s[0:1]
	s_cbranch_vccnz .LBB0_541
	s_waitcnt vmcnt(0) lgkmcnt(0)
	s_barrier
	s_mov_b64 s[0:1], exec
	v_readlane_b32 s4, v254, 2
	v_readlane_b32 s5, v254, 3
	s_nop 1
	s_and_b64 s[4:5], s[0:1], s[4:5]
	s_mov_b64 exec, s[4:5]
	s_cbranch_execz .Llb487_join
	s_getreg_b32 s3, hwreg(HW_REG_XCC_ID, 0, 4)
	v_mov_b32_e32 v1, 0x23fc0
	ds_read_b64 v[16:17], v1
	s_lshl_b32 s3, s3, 6
	s_add_u32 s8, s62, 0x40b800
	s_addc_u32 s9, s63, 0
	v_mov_b32_e32 v1, s3
	v_mov_b32_e32 v3, 1
	global_atomic_add v2, v1, v3, s[8:9] sc0
	s_waitcnt vmcnt(0) lgkmcnt(0)
	v_add_u32_e32 v2, 1, v2
	v_cmp_eq_u32_e32 vcc, v2, v16
	v_mov_b32_e32 v1, 0x400
	s_cbranch_vccz .Llb487_poll
	buffer_wbl2 sc1
	s_waitcnt vmcnt(0)
	global_atomic_add v1, v3, s[8:9]
.Llb487_poll:
	s_mov_b32 s6, 0
.Llb487_spin:
	global_load_dword v2, v1, s[8:9] sc1
	s_waitcnt vmcnt(0)
	v_cmp_ge_u32_e32 vcc, v2, v17
	s_cbranch_vccnz .Llb487_done
	s_sleep 1
	s_add_u32 s6, s6, 1
	s_cmp_lt_u32 s6, 0x100000
	s_cbranch_scc1 .Llb487_spin

.Llb487_join:
	s_mov_b64 exec, s[0:1]
	s_barrier
.LBB0_541:
	s_cmp_lt_i32 s96, 7
	s_cselect_b64 s[0:1], -1, 0
	s_cmp_gt_i32 s97, 6
	s_cselect_b64 s[4:5], -1, 0
	s_and_b64 s[6:7], s[0:1], s[4:5]
	s_andn2_b64 vcc, exec, s[6:7]
	s_cbranch_vccnz .LBB0_576
	s_add_u32 s12, s62, 0x500000
	s_addc_u32 s13, s63, 0
	s_add_u32 s14, s62, 0x510000
	s_addc_u32 s15, s63, 0
	s_add_u32 s8, s62, 0x600000
	s_addc_u32 s9, s63, 0
	s_add_u32 s10, s62, 0x610000
	s_addc_u32 s11, s63, 0
	s_ashr_i32 s3, s2, 31
	s_movk_i32 s0, 0x100
	s_ashr_i32 s36, s33, 31
	v_cmp_gt_u32_e64 s[4:5], s0, v190
	s_waitcnt lgkmcnt(0)
	v_mov_b64_e32 v[2:3], 0x200
	v_mov_b64_e32 v[4:5], 0x1ff
	v_mov_b32_e32 v1, 0x358637bd
	s_mov_b32 s20, 0x800000
	s_mov_b64 s[16:17], s[2:3]
	s_branch .LBB0_545

.LBB0_576:
	s_cmp_gt_i32 s97, 7
	s_cselect_b64 s[0:1], -1, 0
	s_and_b64 s[4:5], s[6:7], s[0:1]
	s_andn2_b64 vcc, exec, s[4:5]
	s_cbranch_vccnz .LBB0_630
	s_waitcnt vmcnt(0) lgkmcnt(0)
	s_barrier
	s_mov_b64 s[4:5], exec
	v_readlane_b32 s6, v254, 2
	v_readlane_b32 s7, v254, 3
	s_nop 1
	s_and_b64 s[6:7], s[4:5], s[6:7]
	s_mov_b64 exec, s[6:7]
	s_cbranch_execz .Llb577_join
	s_getreg_b32 s3, hwreg(HW_REG_XCC_ID, 0, 4)
	v_mov_b32_e32 v1, 0x23fc0
	ds_read_b64 v[16:17], v1
	s_lshl_b32 s3, s3, 6
	s_add_u32 s10, s62, 0x40c000
	s_addc_u32 s11, s63, 0
	v_mov_b32_e32 v1, s3
	v_mov_b32_e32 v3, 1
	global_atomic_add v2, v1, v3, s[10:11] sc0
	s_waitcnt vmcnt(0) lgkmcnt(0)
	v_add_u32_e32 v2, 1, v2
	v_cmp_eq_u32_e32 vcc, v2, v16
	v_mov_b32_e32 v1, 0x400
	s_cbranch_vccz .Llb577_poll
	buffer_wbl2 sc1
	s_waitcnt vmcnt(0)
	global_atomic_add v1, v3, s[10:11]

.LBB0_714:
	s_add_u32 s50, s62, 0x400200
	s_addc_u32 s51, s63, 0
	s_add_u32 s68, s62, 0x400400
	s_addc_u32 s69, s63, 0
	s_add_u32 s70, s62, 0x400500
	s_addc_u32 s71, s63, 0
	s_add_u32 s72, s62, 0x400600
	s_addc_u32 s73, s63, 0
	s_add_u32 s74, s62, 0x400700
	s_addc_u32 s75, s63, 0
	s_add_u32 s76, s62, 0x400800
	s_addc_u32 s77, s63, 0
	v_writelane_b32 v254, s78, 49
	s_add_u32 s78, s62, 0x400900
	s_addc_u32 s79, s63, 0
	s_add_u32 s80, s62, 0x400a00
	s_addc_u32 s81, s63, 0
	s_add_u32 s82, s62, 0x400b00
	s_addc_u32 s83, s63, 0
	s_add_u32 s84, s62, 0x400c00
	s_addc_u32 s85, s63, 0
	s_add_u32 s86, s62, 0x400d00
	s_addc_u32 s87, s63, 0
	s_add_u32 s88, s62, 0x400e00
	s_addc_u32 s89, s63, 0
	s_add_u32 s90, s62, 0x400f00
	s_addc_u32 s91, s63, 0
	s_add_u32 s92, s62, 0x401000
	s_addc_u32 s93, s63, 0
	s_add_u32 s94, s62, 0x401100
	s_addc_u32 s95, s63, 0
	s_add_u32 s46, s62, 0x401200
	s_addc_u32 s47, s63, 0
	s_add_u32 s4, s62, 0x401300
	s_addc_u32 s5, s63, 0
	v_readlane_b32 s6, v254, 38
	s_cmp_eq_u32 s6, 15
	s_cselect_b64 s[8:9], -1, 0
	v_writelane_b32 v254, s8, 43
	s_cmp_eq_u32 s6, 14
	s_nop 0
	v_writelane_b32 v254, s9, 44
	s_cselect_b64 s[8:9], -1, 0
	v_writelane_b32 v254, s8, 41
	s_cmp_eq_u32 s6, 13
	s_nop 0
	v_writelane_b32 v254, s9, 42
	s_cselect_b64 s[8:9], -1, 0
	v_writelane_b32 v254, s8, 46
	s_cmp_eq_u32 s6, 12
	s_nop 0
	v_writelane_b32 v254, s9, 47
	s_cselect_b64 s[8:9], -1, 0
	v_writelane_b32 v254, s8, 50
	s_cmp_eq_u32 s6, 11
	s_nop 0
	v_writelane_b32 v254, s9, 51
	s_cselect_b64 s[8:9], -1, 0
	v_writelane_b32 v254, s8, 52
	s_cmp_eq_u32 s6, 10
	s_nop 0
	v_writelane_b32 v254, s9, 53
	s_cselect_b64 s[8:9], -1, 0
	v_writelane_b32 v254, s8, 54
	s_cmp_eq_u32 s6, 9
	s_nop 0
	v_writelane_b32 v254, s9, 55
	s_cselect_b64 s[8:9], -1, 0
	v_writelane_b32 v254, s8, 56
	s_cmp_eq_u32 s6, 8
	s_nop 0
	v_writelane_b32 v254, s9, 57
	s_cselect_b64 s[8:9], -1, 0
	v_writelane_b32 v254, s8, 58
	s_cmp_eq_u32 s6, 7
	s_nop 0
	v_writelane_b32 v254, s9, 59
	s_cselect_b64 s[8:9], -1, 0
	v_writelane_b32 v254, s8, 60
	s_cmp_eq_u32 s6, 6
	s_nop 0
	v_writelane_b32 v254, s9, 61
	s_cselect_b64 s[8:9], -1, 0
	v_writelane_b32 v254, s8, 62
	s_cmp_eq_u32 s6, 5
	s_nop 0
	v_writelane_b32 v254, s9, 63
	s_cselect_b64 s[8:9], -1, 0
	v_writelane_b32 v255, s8, 0
	s_cmp_eq_u32 s6, 4
	s_nop 0
	v_writelane_b32 v255, s9, 1
	s_cselect_b64 s[8:9], -1, 0
	v_writelane_b32 v255, s8, 2
	s_cmp_eq_u32 s6, 3
	s_nop 0
	v_writelane_b32 v255, s9, 3
	s_cselect_b64 s[8:9], -1, 0
	v_writelane_b32 v255, s8, 4
	s_cmp_eq_u32 s6, 2
	s_nop 0
	v_writelane_b32 v255, s9, 5
	s_cselect_b64 s[8:9], -1, 0
	v_writelane_b32 v255, s8, 6
	s_cmp_eq_u32 s6, 1
	s_nop 0
	v_writelane_b32 v255, s9, 7
	s_cselect_b64 s[8:9], -1, 0
	v_writelane_b32 v255, s8, 8
	s_cmp_eq_u32 s6, 0
	s_nop 0
	v_writelane_b32 v255, s9, 9
	s_cselect_b64 s[8:9], -1, 0
	s_lshl_b32 s6, s6, 8
	s_add_u32 s6, s96, s6
	v_writelane_b32 v255, s8, 10
	s_addc_u32 s7, s97, 0
	s_nop 0
	v_writelane_b32 v255, s9, 11
	s_add_u32 s8, s6, 0x1400
	s_addc_u32 s9, s7, 0
	s_add_u32 s52, s6, 0x2400
	s_addc_u32 s53, s7, 0
	v_writelane_b32 v254, s8, 22
	s_add_u32 s6, s62, 0x403400
	s_addc_u32 s7, s63, 0
	v_writelane_b32 v254, s9, 23
	v_writelane_b32 v254, s6, 4
	s_add_u32 s28, s62, 0x403500
	s_addc_u32 s29, s63, 0
	v_writelane_b32 v254, s7, 5
	s_nop 0
	v_readlane_b32 s6, v254, 39
	v_readlane_b32 s7, v254, 40
	s_cmp_gt_i32 s7, 9
	s_cselect_b64 s[6:7], -1, 0
	s_and_b64 s[8:9], s[42:43], s[6:7]
	s_andn2_b64 vcc, exec, s[8:9]
	s_cbranch_vccnz .LBB0_768
	s_waitcnt vmcnt(0) lgkmcnt(0)
	s_barrier
	s_mov_b64 s[8:9], exec
	v_readlane_b32 s10, v254, 2
	v_readlane_b32 s11, v254, 3
	s_nop 1
	s_and_b64 s[10:11], s[8:9], s[10:11]
	s_mov_b64 exec, s[10:11]
	s_cbranch_execz .Llb715_join
	s_getreg_b32 s17, hwreg(HW_REG_XCC_ID, 0, 4)
	v_mov_b32_e32 v4, 0x23fc0
	ds_read_b64 v[2:3], v4
	s_lshl_b32 s17, s17, 6
	s_add_u32 s12, s62, 0x40c800
	s_addc_u32 s13, s63, 0
	v_mov_b32_e32 v4, s17
	v_mov_b32_e32 v18, 1
	global_atomic_add v17, v4, v18, s[12:13] sc0
	s_waitcnt vmcnt(0) lgkmcnt(0)
	v_add_u32_e32 v17, 1, v17
	v_cmp_eq_u32_e32 vcc, v17, v2
	v_mov_b32_e32 v4, 0x400
	s_cbranch_vccz .Llb715_poll
	buffer_wbl2 sc1
	s_waitcnt vmcnt(0)
	global_atomic_add v4, v18, s[12:13]
.Llb715_poll:
	s_mov_b32 s16, 0
.Llb715_spin:
	global_load_dword v17, v4, s[12:13] sc1
	s_waitcnt vmcnt(0)
	v_cmp_ge_u32_e32 vcc, v17, v3
	s_cbranch_vccnz .Llb715_done
	s_sleep 1
	s_add_u32 s16, s16, 1
	s_cmp_lt_u32 s16, 0x100000
	s_cbranch_scc1 .Llb715_spin

.Llb715_join:
	s_mov_b64 exec, s[8:9]
	s_barrier

.LBB0_864:
	v_readlane_b32 s6, v254, 39
	v_readlane_b32 s7, v254, 40
	s_cmp_gt_i32 s7, 11
	s_cselect_b64 s[6:7], -1, 0
	s_and_b64 s[8:9], s[42:43], s[6:7]
	s_andn2_b64 vcc, exec, s[8:9]
	s_cbranch_vccnz .LBB0_918
	s_waitcnt vmcnt(0) lgkmcnt(0)
	s_barrier
	s_mov_b64 s[8:9], exec
	v_readlane_b32 s10, v254, 2
	v_readlane_b32 s11, v254, 3
	s_nop 1
	s_and_b64 s[10:11], s[8:9], s[10:11]
	s_mov_b64 exec, s[10:11]
	s_cbranch_execz .Llb865_join
	s_getreg_b32 s17, hwreg(HW_REG_XCC_ID, 0, 4)
	v_mov_b32_e32 v4, 0x23fc0
	ds_read_b64 v[2:3], v4
	s_lshl_b32 s17, s17, 6
	s_add_u32 s12, s62, 0x40d000
	s_addc_u32 s13, s63, 0
	v_mov_b32_e32 v4, s17
	v_mov_b32_e32 v18, 1
	global_atomic_add v17, v4, v18, s[12:13] sc0
	s_waitcnt vmcnt(0) lgkmcnt(0)
	v_add_u32_e32 v17, 1, v17
	v_cmp_eq_u32_e32 vcc, v17, v2
	v_mov_b32_e32 v4, 0x400
	s_cbranch_vccz .Llb865_poll
	buffer_wbl2 sc1
	s_waitcnt vmcnt(0)
	global_atomic_add v4, v18, s[12:13]
